# P1 mods table spread over all workgroups (64 consecutive elements per wave: wave 0 everywhere, wave 1 on workgroups 0..175) instead of workgroups 0..53
# baseline (speedup 1.0000x reference)
; __global__ void __launch_bounds__(512, 2) fwd_megakernel(Params Parg) {
;     ...
;         for (int i = bid * 512 + tid; i < 3 * NMOD * D; i += G * 512) {
;             const int ms = i / (NMOD * D), n = i % (NMOD * D); float a = b_mod[n];
; #pragma unroll
;             for (int p = 0; p < 8; ++p) a += part[(p * 3 + ms) * (NMOD * D) + n];
;             mods[i] = a;
;         }
.LBB0_222:
	s_or_b64 exec, exec, s[6:7]
	s_mov_b64 s[8:9], s[0:1]
	s_waitcnt lgkmcnt(0)
	s_barrier
	s_load_dwordx2 s[20:21], s[8:9], 0xd0
	v_mov_b32_e32 v2, v176
	s_load_dwordx2 s[6:7], s[8:9], 0x0
	s_load_dwordx2 s[22:23], s[8:9], 0x28
	v_readfirstlane_b32 s3, v2
	s_waitcnt lgkmcnt(0)
	s_add_u32 s10, s20, 0x3d20000
	s_addc_u32 s11, s21, 0
	s_lshl_b32 s4, s2, 9
	v_writelane_b32 v254, s4, 3
	v_and_b32_e32 v0, 63, v2
	v_lshrrev_b32_e32 v1, 6, v2
	v_lshl_add_u32 v0, v1, 14, v0
	s_lshl_b32 s12, s2, 6
	v_add_u32_e32 v0, s12, v0
	s_movk_i32 s4, 0x6c00
	v_cmp_gt_i32_e32 vcc, s4, v0
	s_and_saveexec_b64 s[14:15], vcc
	s_cbranch_execz .LBB0_225
	s_add_u32 s16, s20, 0x3d00000
	s_addc_u32 s17, s21, 0
	s_lshl_b32 s4, s28, 9
	s_mov_b64 s[18:19], 0
	s_mov_b32 s5, 0x38e38e39
	s_movk_i32 s12, 0x6bff
